# v38 + MLA bodies causal mask rewrite (inline-constant compares, three results in flight)
# baseline (speedup 1.0000x reference)
.Lskip_v2_2_p0:
.LBB0_2155_p0:
	s_sub_i32 s61, s75, 63
	s_cmp_gt_i32 s61, s25
	s_cbranch_scc1 .Lnovis_p0
	s_bitcmp1_b32 s60, 0
	s_cselect_b32 s60, 0x6400, 0
	v_add_u32_e32 v0, s60, v200
	s_setprio 1
	ds_read_b128 v[238:241], v0
	ds_read_b128 v[244:247], v0 offset:32
	ds_read_b128 v[248:251], v0 offset:12800
	ds_read_b128 v[8:11], v0 offset:12832
	ds_read_b128 v[12:15], v0 offset:64
	s_waitcnt lgkmcnt(4)
	v_mfma_f32_32x32x16_bf16 v[96:111], v[238:241], v[128:131], v[80:95]
	ds_read_b128 v[238:241], v0 offset:12864
	s_waitcnt lgkmcnt(4)
	v_mfma_f32_32x32x16_bf16 v[96:111], v[244:247], v[132:135], v[96:111]
	ds_read_b128 v[244:247], v0 offset:96
	s_waitcnt lgkmcnt(4)
	v_mfma_f32_32x32x16_bf16 v[112:127], v[248:251], v[128:131], v[80:95]
	ds_read_b128 v[248:251], v0 offset:12896
	s_waitcnt lgkmcnt(4)
	v_mfma_f32_32x32x16_bf16 v[112:127], v[8:11], v[132:135], v[112:127]
	ds_read_b128 v[8:11], v0 offset:128
	s_waitcnt lgkmcnt(4)
	v_mfma_f32_32x32x16_bf16 v[96:111], v[12:15], v[136:139], v[96:111]
	ds_read_b128 v[12:15], v0 offset:12928
	s_waitcnt lgkmcnt(4)
	v_mfma_f32_32x32x16_bf16 v[112:127], v[238:241], v[136:139], v[112:127]
	ds_read_b128 v[238:241], v0 offset:160
	s_waitcnt lgkmcnt(4)
	v_mfma_f32_32x32x16_bf16 v[96:111], v[244:247], v[140:143], v[96:111]
	ds_read_b128 v[244:247], v0 offset:12960
	s_waitcnt lgkmcnt(4)
	v_mfma_f32_32x32x16_bf16 v[112:127], v[248:251], v[140:143], v[112:127]
	ds_read_b128 v[248:251], v0 offset:192
	s_waitcnt lgkmcnt(4)
	v_mfma_f32_32x32x16_bf16 v[96:111], v[8:11], v[144:147], v[96:111]
	ds_read_b128 v[8:11], v0 offset:12992
	s_waitcnt lgkmcnt(4)
	v_mfma_f32_32x32x16_bf16 v[112:127], v[12:15], v[144:147], v[112:127]
	ds_read_b128 v[12:15], v0 offset:224
	s_waitcnt lgkmcnt(4)
	v_mfma_f32_32x32x16_bf16 v[96:111], v[238:241], v[148:151], v[96:111]
	ds_read_b128 v[238:241], v0 offset:13024
	s_waitcnt lgkmcnt(4)
	v_mfma_f32_32x32x16_bf16 v[112:127], v[244:247], v[148:151], v[112:127]
	ds_read_b128 v[244:247], v0 offset:256
	s_waitcnt lgkmcnt(4)
	v_mfma_f32_32x32x16_bf16 v[96:111], v[248:251], v[152:155], v[96:111]
	ds_read_b128 v[248:251], v0 offset:13056
	s_waitcnt lgkmcnt(4)
	v_mfma_f32_32x32x16_bf16 v[112:127], v[8:11], v[152:155], v[112:127]
	ds_read_b128 v[8:11], v0 offset:288
	s_waitcnt lgkmcnt(4)
	v_mfma_f32_32x32x16_bf16 v[96:111], v[12:15], v[156:159], v[96:111]
	ds_read_b128 v[12:15], v0 offset:13088
	s_waitcnt lgkmcnt(4)
	v_mfma_f32_32x32x16_bf16 v[112:127], v[238:241], v[156:159], v[112:127]
	ds_read_b128 v[238:241], v0 offset:320
	s_waitcnt lgkmcnt(4)
	v_mfma_f32_32x32x16_bf16 v[96:111], v[244:247], v[160:163], v[96:111]
	ds_read_b128 v[244:247], v0 offset:13120
	s_waitcnt lgkmcnt(4)
	v_mfma_f32_32x32x16_bf16 v[112:127], v[248:251], v[160:163], v[112:127]
	ds_read_b128 v[248:251], v0 offset:352
	s_waitcnt lgkmcnt(4)
	v_mfma_f32_32x32x16_bf16 v[96:111], v[8:11], v[164:167], v[96:111]
	ds_read_b128 v[8:11], v0 offset:13152
	s_waitcnt lgkmcnt(4)
	v_mfma_f32_32x32x16_bf16 v[112:127], v[12:15], v[164:167], v[112:127]
	s_waitcnt lgkmcnt(3)
	v_mfma_f32_32x32x16_bf16 v[96:111], v[238:241], v[168:171], v[96:111]
	s_waitcnt lgkmcnt(2)
	v_mfma_f32_32x32x16_bf16 v[112:127], v[244:247], v[168:171], v[112:127]
	s_waitcnt lgkmcnt(1)
	v_mfma_f32_32x32x16_bf16 v[96:111], v[248:251], v[172:175], v[96:111]
	s_waitcnt lgkmcnt(0)
	v_mfma_f32_32x32x16_bf16 v[112:127], v[8:11], v[172:175], v[112:127]
	s_setprio 0
	s_cmp_le_i32 s75, s68
	s_cbranch_scc1 .Lmaskdone_p0
	v_add_u32_e32 v0, s75, v201
	v_sub_u32_e32 v0, v0, v197
	s_nop 1
	v_cmp_ge_i32_e32 vcc, 63, v0
	v_cmp_gt_i32_e64 s[22:23], 63, v0
	v_cmp_ge_i32_e64 s[96:97], 61, v0
	v_cndmask_b32_e32 v96, v194, v96, vcc
	v_cndmask_b32_e64 v97, v194, v97, s[22:23]
	v_cndmask_b32_e64 v98, v194, v98, s[96:97]
	v_cmp_ge_i32_e32 vcc, 60, v0
	v_cmp_ge_i32_e64 s[22:23], 55, v0
	v_cmp_ge_i32_e64 s[96:97], 54, v0
	v_cndmask_b32_e32 v99, v194, v99, vcc
	v_cndmask_b32_e64 v100, v194, v100, s[22:23]
	v_cndmask_b32_e64 v101, v194, v101, s[96:97]
	v_cmp_ge_i32_e32 vcc, 53, v0
	v_cmp_ge_i32_e64 s[22:23], 52, v0
	v_cmp_ge_i32_e64 s[96:97], 47, v0
	v_cndmask_b32_e32 v102, v194, v102, vcc
	v_cndmask_b32_e64 v103, v194, v103, s[22:23]
	v_cndmask_b32_e64 v104, v194, v104, s[96:97]
	v_cmp_ge_i32_e32 vcc, 46, v0
	v_cmp_ge_i32_e64 s[22:23], 45, v0
	v_cmp_ge_i32_e64 s[96:97], 44, v0
	v_cndmask_b32_e32 v105, v194, v105, vcc
	v_cndmask_b32_e64 v106, v194, v106, s[22:23]
	v_cndmask_b32_e64 v107, v194, v107, s[96:97]
	v_cmp_ge_i32_e32 vcc, 39, v0
	v_cmp_ge_i32_e64 s[22:23], 38, v0
	v_cmp_ge_i32_e64 s[96:97], 37, v0
	v_cndmask_b32_e32 v108, v194, v108, vcc
	v_cndmask_b32_e64 v109, v194, v109, s[22:23]
	v_cndmask_b32_e64 v110, v194, v110, s[96:97]
	v_cmp_ge_i32_e32 vcc, 36, v0
	v_cmp_ge_i32_e64 s[22:23], 31, v0
	v_cmp_ge_i32_e64 s[96:97], 30, v0
	v_cndmask_b32_e32 v111, v194, v111, vcc
	v_cndmask_b32_e64 v112, v194, v112, s[22:23]
	v_cndmask_b32_e64 v113, v194, v113, s[96:97]
	v_cmp_ge_i32_e32 vcc, 29, v0
	v_cmp_ge_i32_e64 s[22:23], 28, v0
	v_cmp_ge_i32_e64 s[96:97], 23, v0
	v_cndmask_b32_e32 v114, v194, v114, vcc
	v_cndmask_b32_e64 v115, v194, v115, s[22:23]
	v_cndmask_b32_e64 v116, v194, v116, s[96:97]
	v_cmp_ge_i32_e32 vcc, 22, v0
	v_cmp_ge_i32_e64 s[22:23], 21, v0
	v_cmp_ge_i32_e64 s[96:97], 20, v0
	v_cndmask_b32_e32 v117, v194, v117, vcc
	v_cndmask_b32_e64 v118, v194, v118, s[22:23]
	v_cndmask_b32_e64 v119, v194, v119, s[96:97]
	v_cmp_ge_i32_e32 vcc, 15, v0
	v_cmp_ge_i32_e64 s[22:23], 14, v0
	v_cmp_ge_i32_e64 s[96:97], 13, v0
	v_cndmask_b32_e32 v120, v194, v120, vcc
	v_cndmask_b32_e64 v121, v194, v121, s[22:23]
	v_cndmask_b32_e64 v122, v194, v122, s[96:97]
	v_cmp_ge_i32_e32 vcc, 12, v0
	v_cmp_ge_i32_e64 s[22:23], 7, v0
	v_cmp_ge_i32_e64 s[96:97], 6, v0
	v_cndmask_b32_e32 v123, v194, v123, vcc
	v_cndmask_b32_e64 v124, v194, v124, s[22:23]
	v_cndmask_b32_e64 v125, v194, v125, s[96:97]
	v_cmp_ge_i32_e32 vcc, 5, v0
	v_cmp_ge_i32_e64 s[22:23], 4, v0
	s_nop 0
	v_cndmask_b32_e32 v126, v194, v126, vcc
	v_cndmask_b32_e64 v127, v194, v127, s[22:23]

.Lskip_v2_2_ba:
.LBB0_2155_ba:
	s_sub_i32 s61, s75, 63
	s_cmp_gt_i32 s61, s25
	s_cbranch_scc1 .Lnovis_ba
	s_bitcmp1_b32 s60, 0
	s_cselect_b32 s60, 0x6400, 0
	v_add_u32_e32 v0, s60, v200
	s_setprio 1
	ds_read_b128 v[238:241], v0
	ds_read_b128 v[244:247], v0 offset:32
	ds_read_b128 v[248:251], v0 offset:12800
	ds_read_b128 v[8:11], v0 offset:12832
	ds_read_b128 v[12:15], v0 offset:64
	s_waitcnt lgkmcnt(4)
	v_mfma_f32_32x32x16_bf16 v[206:221], v[238:241], v[128:131], v[80:95]
	ds_read_b128 v[238:241], v0 offset:12864
	v_exp_f32_e32 v96, v96
	v_exp_f32_e32 v97, v97
	v_exp_f32_e32 v98, v98
	v_exp_f32_e32 v99, v99
	s_waitcnt lgkmcnt(4)
	v_mfma_f32_32x32x16_bf16 v[206:221], v[244:247], v[132:135], v[206:221]
	ds_read_b128 v[244:247], v0 offset:96
	v_exp_f32_e32 v100, v100
	v_exp_f32_e32 v101, v101
	v_exp_f32_e32 v102, v102
	s_waitcnt lgkmcnt(4)
	v_mfma_f32_32x32x16_bf16 v[222:237], v[248:251], v[128:131], v[80:95]
	ds_read_b128 v[248:251], v0 offset:12896
	v_exp_f32_e32 v103, v103
	v_exp_f32_e32 v104, v104
	v_exp_f32_e32 v105, v105
	s_waitcnt lgkmcnt(4)
	v_mfma_f32_32x32x16_bf16 v[222:237], v[8:11], v[132:135], v[222:237]
	ds_read_b128 v[8:11], v0 offset:128
	v_exp_f32_e32 v106, v106
	v_exp_f32_e32 v107, v107
	v_exp_f32_e32 v108, v108
	v_exp_f32_e32 v109, v109
	s_waitcnt lgkmcnt(4)
	v_mfma_f32_32x32x16_bf16 v[206:221], v[12:15], v[136:139], v[206:221]
	ds_read_b128 v[12:15], v0 offset:12928
	v_exp_f32_e32 v110, v110
	v_exp_f32_e32 v111, v111
	v_add_f32_e32 v252, v96, v97
	s_waitcnt lgkmcnt(4)
	v_mfma_f32_32x32x16_bf16 v[222:237], v[238:241], v[136:139], v[222:237]
	ds_read_b128 v[238:241], v0 offset:160
	v_add_f32_e32 v253, v98, v99
	v_add_f32_e32 v254, v100, v101
	v_add_f32_e32 v205, v102, v103
	s_waitcnt lgkmcnt(4)
	v_mfma_f32_32x32x16_bf16 v[206:221], v[244:247], v[140:143], v[206:221]
	ds_read_b128 v[244:247], v0 offset:12960
	v_cvt_pk_bf16_f32 v96, v96, v97
	v_cvt_pk_bf16_f32 v97, v98, v99
	v_cvt_pk_bf16_f32 v98, v100, v101
	v_cvt_pk_bf16_f32 v99, v102, v103
	s_waitcnt lgkmcnt(4)
	v_mfma_f32_32x32x16_bf16 v[222:237], v[248:251], v[140:143], v[222:237]
	ds_read_b128 v[248:251], v0 offset:192
	v_exp_f32_e32 v112, v112
	v_exp_f32_e32 v113, v113
	v_exp_f32_e32 v114, v114
	s_waitcnt lgkmcnt(4)
	v_mfma_f32_32x32x16_bf16 v[206:221], v[8:11], v[144:147], v[206:221]
	ds_read_b128 v[8:11], v0 offset:12992
	v_exp_f32_e32 v115, v115
	v_exp_f32_e32 v116, v116
	v_exp_f32_e32 v117, v117
	s_waitcnt lgkmcnt(4)
	v_mfma_f32_32x32x16_bf16 v[222:237], v[12:15], v[144:147], v[222:237]
	ds_read_b128 v[12:15], v0 offset:224
	v_exp_f32_e32 v118, v118
	v_exp_f32_e32 v119, v119
	v_add_f32_e32 v252, v252, v104
	v_add_f32_e32 v253, v253, v105
	s_waitcnt lgkmcnt(4)
	v_mfma_f32_32x32x16_bf16 v[206:221], v[238:241], v[148:151], v[206:221]
	ds_read_b128 v[238:241], v0 offset:13024
	v_add_f32_e32 v254, v254, v106
	v_add_f32_e32 v205, v205, v107
	v_add_f32_e32 v252, v252, v108
	s_waitcnt lgkmcnt(4)
	v_mfma_f32_32x32x16_bf16 v[222:237], v[244:247], v[148:151], v[222:237]
	ds_read_b128 v[244:247], v0 offset:256
	v_add_f32_e32 v253, v253, v109
	v_add_f32_e32 v254, v254, v110
	v_add_f32_e32 v205, v205, v111
	s_waitcnt lgkmcnt(4)
	v_mfma_f32_32x32x16_bf16 v[206:221], v[248:251], v[152:155], v[206:221]
	ds_read_b128 v[248:251], v0 offset:13056
	v_cvt_pk_bf16_f32 v104, v104, v105
	v_cvt_pk_bf16_f32 v105, v106, v107
	v_cvt_pk_bf16_f32 v106, v108, v109
	v_cvt_pk_bf16_f32 v107, v110, v111
	s_waitcnt lgkmcnt(4)
	v_mfma_f32_32x32x16_bf16 v[222:237], v[8:11], v[152:155], v[222:237]
	ds_read_b128 v[8:11], v0 offset:288
	v_exp_f32_e32 v120, v120
	v_exp_f32_e32 v121, v121
	v_exp_f32_e32 v122, v122
	s_waitcnt lgkmcnt(4)
	v_mfma_f32_32x32x16_bf16 v[206:221], v[12:15], v[156:159], v[206:221]
	ds_read_b128 v[12:15], v0 offset:13088
	v_exp_f32_e32 v123, v123
	v_exp_f32_e32 v124, v124
	v_exp_f32_e32 v125, v125
	s_waitcnt lgkmcnt(4)
	v_mfma_f32_32x32x16_bf16 v[222:237], v[238:241], v[156:159], v[222:237]
	ds_read_b128 v[238:241], v0 offset:320
	v_exp_f32_e32 v126, v126
	v_exp_f32_e32 v127, v127
	v_add_f32_e32 v252, v252, v112
	v_add_f32_e32 v253, v253, v113
	s_waitcnt lgkmcnt(4)
	v_mfma_f32_32x32x16_bf16 v[206:221], v[244:247], v[160:163], v[206:221]
	ds_read_b128 v[244:247], v0 offset:13120
	v_add_f32_e32 v254, v254, v114
	v_add_f32_e32 v205, v205, v115
	v_add_f32_e32 v252, v252, v116
	s_waitcnt lgkmcnt(4)
	v_mfma_f32_32x32x16_bf16 v[222:237], v[248:251], v[160:163], v[222:237]
	ds_read_b128 v[248:251], v0 offset:352
	v_add_f32_e32 v253, v253, v117
	v_add_f32_e32 v254, v254, v118
	v_add_f32_e32 v205, v205, v119
	s_waitcnt lgkmcnt(4)
	v_mfma_f32_32x32x16_bf16 v[206:221], v[8:11], v[164:167], v[206:221]
	ds_read_b128 v[8:11], v0 offset:13152
	v_cvt_pk_bf16_f32 v112, v112, v113
	v_cvt_pk_bf16_f32 v113, v114, v115
	v_cvt_pk_bf16_f32 v114, v116, v117
	v_cvt_pk_bf16_f32 v115, v118, v119
	s_waitcnt lgkmcnt(4)
	v_mfma_f32_32x32x16_bf16 v[222:237], v[12:15], v[164:167], v[222:237]
	v_add_f32_e32 v252, v252, v120
	v_add_f32_e32 v253, v253, v121
	v_add_f32_e32 v254, v254, v122
	s_waitcnt lgkmcnt(3)
	v_mfma_f32_32x32x16_bf16 v[206:221], v[238:241], v[168:171], v[206:221]
	v_add_f32_e32 v205, v205, v123
	v_add_f32_e32 v252, v252, v124
	v_add_f32_e32 v253, v253, v125
	s_waitcnt lgkmcnt(2)
	v_mfma_f32_32x32x16_bf16 v[222:237], v[244:247], v[168:171], v[222:237]
	v_add_f32_e32 v254, v254, v126
	v_add_f32_e32 v205, v205, v127
	v_cvt_pk_bf16_f32 v120, v120, v121
	v_cvt_pk_bf16_f32 v121, v122, v123
	s_waitcnt lgkmcnt(1)
	v_mfma_f32_32x32x16_bf16 v[206:221], v[248:251], v[172:175], v[206:221]
	v_cvt_pk_bf16_f32 v122, v124, v125
	v_cvt_pk_bf16_f32 v123, v126, v127
	v_add_f32_e32 v252, v252, v253
	s_waitcnt lgkmcnt(0)
	v_mfma_f32_32x32x16_bf16 v[222:237], v[8:11], v[172:175], v[222:237]
	v_add_f32_e32 v254, v254, v205
	v_add_f32_e32 v252, v252, v254
	v_add_f32_e32 v2, v2, v252
	s_setprio 0
	s_cmp_le_i32 s75, s68
	s_cbranch_scc1 .Lmaskdone_ba
	v_add_u32_e32 v0, s75, v201
	v_sub_u32_e32 v0, v0, v197
	s_nop 1
	v_cmp_ge_i32_e32 vcc, 63, v0
	v_cmp_gt_i32_e64 s[22:23], 63, v0
	v_cmp_ge_i32_e64 s[96:97], 61, v0
	v_cndmask_b32_e32 v206, v194, v206, vcc
	v_cndmask_b32_e64 v207, v194, v207, s[22:23]
	v_cndmask_b32_e64 v208, v194, v208, s[96:97]
	v_cmp_ge_i32_e32 vcc, 60, v0
	v_cmp_ge_i32_e64 s[22:23], 55, v0
	v_cmp_ge_i32_e64 s[96:97], 54, v0
	v_cndmask_b32_e32 v209, v194, v209, vcc
	v_cndmask_b32_e64 v210, v194, v210, s[22:23]
	v_cndmask_b32_e64 v211, v194, v211, s[96:97]
	v_cmp_ge_i32_e32 vcc, 53, v0
	v_cmp_ge_i32_e64 s[22:23], 52, v0
	v_cmp_ge_i32_e64 s[96:97], 47, v0
	v_cndmask_b32_e32 v212, v194, v212, vcc
	v_cndmask_b32_e64 v213, v194, v213, s[22:23]
	v_cndmask_b32_e64 v214, v194, v214, s[96:97]
	v_cmp_ge_i32_e32 vcc, 46, v0
	v_cmp_ge_i32_e64 s[22:23], 45, v0
	v_cmp_ge_i32_e64 s[96:97], 44, v0
	v_cndmask_b32_e32 v215, v194, v215, vcc
	v_cndmask_b32_e64 v216, v194, v216, s[22:23]
	v_cndmask_b32_e64 v217, v194, v217, s[96:97]
	v_cmp_ge_i32_e32 vcc, 39, v0
	v_cmp_ge_i32_e64 s[22:23], 38, v0
	v_cmp_ge_i32_e64 s[96:97], 37, v0
	v_cndmask_b32_e32 v218, v194, v218, vcc
	v_cndmask_b32_e64 v219, v194, v219, s[22:23]
	v_cndmask_b32_e64 v220, v194, v220, s[96:97]
	v_cmp_ge_i32_e32 vcc, 36, v0
	v_cmp_ge_i32_e64 s[22:23], 31, v0
	v_cmp_ge_i32_e64 s[96:97], 30, v0
	v_cndmask_b32_e32 v221, v194, v221, vcc
	v_cndmask_b32_e64 v222, v194, v222, s[22:23]
	v_cndmask_b32_e64 v223, v194, v223, s[96:97]
	v_cmp_ge_i32_e32 vcc, 29, v0
	v_cmp_ge_i32_e64 s[22:23], 28, v0
	v_cmp_ge_i32_e64 s[96:97], 23, v0
	v_cndmask_b32_e32 v224, v194, v224, vcc
	v_cndmask_b32_e64 v225, v194, v225, s[22:23]
	v_cndmask_b32_e64 v226, v194, v226, s[96:97]
	v_cmp_ge_i32_e32 vcc, 22, v0
	v_cmp_ge_i32_e64 s[22:23], 21, v0
	v_cmp_ge_i32_e64 s[96:97], 20, v0
	v_cndmask_b32_e32 v227, v194, v227, vcc
	v_cndmask_b32_e64 v228, v194, v228, s[22:23]
	v_cndmask_b32_e64 v229, v194, v229, s[96:97]
	v_cmp_ge_i32_e32 vcc, 15, v0
	v_cmp_ge_i32_e64 s[22:23], 14, v0
	v_cmp_ge_i32_e64 s[96:97], 13, v0
	v_cndmask_b32_e32 v230, v194, v230, vcc
	v_cndmask_b32_e64 v231, v194, v231, s[22:23]
	v_cndmask_b32_e64 v232, v194, v232, s[96:97]
	v_cmp_ge_i32_e32 vcc, 12, v0
	v_cmp_ge_i32_e64 s[22:23], 7, v0
	v_cmp_ge_i32_e64 s[96:97], 6, v0
	v_cndmask_b32_e32 v233, v194, v233, vcc
	v_cndmask_b32_e64 v234, v194, v234, s[22:23]
	v_cndmask_b32_e64 v235, v194, v235, s[96:97]
	v_cmp_ge_i32_e32 vcc, 5, v0
	v_cmp_ge_i32_e64 s[22:23], 4, v0
	s_nop 0
	v_cndmask_b32_e32 v236, v194, v236, vcc
	v_cndmask_b32_e64 v237, v194, v237, s[22:23]

.Lskip_v2_2_ab:
.LBB0_2155_ab:
	s_sub_i32 s61, s75, 63
	s_cmp_gt_i32 s61, s25
	s_cbranch_scc1 .Lnovis_ab
	s_bitcmp1_b32 s60, 0
	s_cselect_b32 s60, 0x6400, 0
	v_add_u32_e32 v0, s60, v200
	s_setprio 1
	ds_read_b128 v[238:241], v0
	ds_read_b128 v[244:247], v0 offset:32
	ds_read_b128 v[248:251], v0 offset:12800
	ds_read_b128 v[8:11], v0 offset:12832
	ds_read_b128 v[12:15], v0 offset:64
	s_waitcnt lgkmcnt(4)
	v_mfma_f32_32x32x16_bf16 v[96:111], v[238:241], v[128:131], v[80:95]
	ds_read_b128 v[238:241], v0 offset:12864
	v_exp_f32_e32 v206, v206
	v_exp_f32_e32 v207, v207
	v_exp_f32_e32 v208, v208
	v_exp_f32_e32 v209, v209
	s_waitcnt lgkmcnt(4)
	v_mfma_f32_32x32x16_bf16 v[96:111], v[244:247], v[132:135], v[96:111]
	ds_read_b128 v[244:247], v0 offset:96
	v_exp_f32_e32 v210, v210
	v_exp_f32_e32 v211, v211
	v_exp_f32_e32 v212, v212
	s_waitcnt lgkmcnt(4)
	v_mfma_f32_32x32x16_bf16 v[112:127], v[248:251], v[128:131], v[80:95]
	ds_read_b128 v[248:251], v0 offset:12896
	v_exp_f32_e32 v213, v213
	v_exp_f32_e32 v214, v214
	v_exp_f32_e32 v215, v215
	s_waitcnt lgkmcnt(4)
	v_mfma_f32_32x32x16_bf16 v[112:127], v[8:11], v[132:135], v[112:127]
	ds_read_b128 v[8:11], v0 offset:128
	v_exp_f32_e32 v216, v216
	v_exp_f32_e32 v217, v217
	v_exp_f32_e32 v218, v218
	v_exp_f32_e32 v219, v219
	s_waitcnt lgkmcnt(4)
	v_mfma_f32_32x32x16_bf16 v[96:111], v[12:15], v[136:139], v[96:111]
	ds_read_b128 v[12:15], v0 offset:12928
	v_exp_f32_e32 v220, v220
	v_exp_f32_e32 v221, v221
	v_add_f32_e32 v252, v206, v207
	s_waitcnt lgkmcnt(4)
	v_mfma_f32_32x32x16_bf16 v[112:127], v[238:241], v[136:139], v[112:127]
	ds_read_b128 v[238:241], v0 offset:160
	v_add_f32_e32 v253, v208, v209
	v_add_f32_e32 v254, v210, v211
	v_add_f32_e32 v205, v212, v213
	s_waitcnt lgkmcnt(4)
	v_mfma_f32_32x32x16_bf16 v[96:111], v[244:247], v[140:143], v[96:111]
	ds_read_b128 v[244:247], v0 offset:12960
	v_cvt_pk_bf16_f32 v206, v206, v207
	v_cvt_pk_bf16_f32 v207, v208, v209
	v_cvt_pk_bf16_f32 v208, v210, v211
	v_cvt_pk_bf16_f32 v209, v212, v213
	s_waitcnt lgkmcnt(4)
	v_mfma_f32_32x32x16_bf16 v[112:127], v[248:251], v[140:143], v[112:127]
	ds_read_b128 v[248:251], v0 offset:192
	v_exp_f32_e32 v222, v222
	v_exp_f32_e32 v223, v223
	v_exp_f32_e32 v224, v224
	s_waitcnt lgkmcnt(4)
	v_mfma_f32_32x32x16_bf16 v[96:111], v[8:11], v[144:147], v[96:111]
	ds_read_b128 v[8:11], v0 offset:12992
	v_exp_f32_e32 v225, v225
	v_exp_f32_e32 v226, v226
	v_exp_f32_e32 v227, v227
	s_waitcnt lgkmcnt(4)
	v_mfma_f32_32x32x16_bf16 v[112:127], v[12:15], v[144:147], v[112:127]
	ds_read_b128 v[12:15], v0 offset:224
	v_exp_f32_e32 v228, v228
	v_exp_f32_e32 v229, v229
	v_add_f32_e32 v252, v252, v214
	v_add_f32_e32 v253, v253, v215
	s_waitcnt lgkmcnt(4)
	v_mfma_f32_32x32x16_bf16 v[96:111], v[238:241], v[148:151], v[96:111]
	ds_read_b128 v[238:241], v0 offset:13024
	v_add_f32_e32 v254, v254, v216
	v_add_f32_e32 v205, v205, v217
	v_add_f32_e32 v252, v252, v218
	s_waitcnt lgkmcnt(4)
	v_mfma_f32_32x32x16_bf16 v[112:127], v[244:247], v[148:151], v[112:127]
	ds_read_b128 v[244:247], v0 offset:256
	v_add_f32_e32 v253, v253, v219
	v_add_f32_e32 v254, v254, v220
	v_add_f32_e32 v205, v205, v221
	s_waitcnt lgkmcnt(4)
	v_mfma_f32_32x32x16_bf16 v[96:111], v[248:251], v[152:155], v[96:111]
	ds_read_b128 v[248:251], v0 offset:13056
	v_cvt_pk_bf16_f32 v214, v214, v215
	v_cvt_pk_bf16_f32 v215, v216, v217
	v_cvt_pk_bf16_f32 v216, v218, v219
	v_cvt_pk_bf16_f32 v217, v220, v221
	s_waitcnt lgkmcnt(4)
	v_mfma_f32_32x32x16_bf16 v[112:127], v[8:11], v[152:155], v[112:127]
	ds_read_b128 v[8:11], v0 offset:288
	v_exp_f32_e32 v230, v230
	v_exp_f32_e32 v231, v231
	v_exp_f32_e32 v232, v232
	s_waitcnt lgkmcnt(4)
	v_mfma_f32_32x32x16_bf16 v[96:111], v[12:15], v[156:159], v[96:111]
	ds_read_b128 v[12:15], v0 offset:13088
	v_exp_f32_e32 v233, v233
	v_exp_f32_e32 v234, v234
	v_exp_f32_e32 v235, v235
	s_waitcnt lgkmcnt(4)
	v_mfma_f32_32x32x16_bf16 v[112:127], v[238:241], v[156:159], v[112:127]
	ds_read_b128 v[238:241], v0 offset:320
	v_exp_f32_e32 v236, v236
	v_exp_f32_e32 v237, v237
	v_add_f32_e32 v252, v252, v222
	v_add_f32_e32 v253, v253, v223
	s_waitcnt lgkmcnt(4)
	v_mfma_f32_32x32x16_bf16 v[96:111], v[244:247], v[160:163], v[96:111]
	ds_read_b128 v[244:247], v0 offset:13120
	v_add_f32_e32 v254, v254, v224
	v_add_f32_e32 v205, v205, v225
	v_add_f32_e32 v252, v252, v226
	s_waitcnt lgkmcnt(4)
	v_mfma_f32_32x32x16_bf16 v[112:127], v[248:251], v[160:163], v[112:127]
	ds_read_b128 v[248:251], v0 offset:352
	v_add_f32_e32 v253, v253, v227
	v_add_f32_e32 v254, v254, v228
	v_add_f32_e32 v205, v205, v229
	s_waitcnt lgkmcnt(4)
	v_mfma_f32_32x32x16_bf16 v[96:111], v[8:11], v[164:167], v[96:111]
	ds_read_b128 v[8:11], v0 offset:13152
	v_cvt_pk_bf16_f32 v222, v222, v223
	v_cvt_pk_bf16_f32 v223, v224, v225
	v_cvt_pk_bf16_f32 v224, v226, v227
	v_cvt_pk_bf16_f32 v225, v228, v229
	s_waitcnt lgkmcnt(4)
	v_mfma_f32_32x32x16_bf16 v[112:127], v[12:15], v[164:167], v[112:127]
	v_add_f32_e32 v252, v252, v230
	v_add_f32_e32 v253, v253, v231
	v_add_f32_e32 v254, v254, v232
	s_waitcnt lgkmcnt(3)
	v_mfma_f32_32x32x16_bf16 v[96:111], v[238:241], v[168:171], v[96:111]
	v_add_f32_e32 v205, v205, v233
	v_add_f32_e32 v252, v252, v234
	v_add_f32_e32 v253, v253, v235
	s_waitcnt lgkmcnt(2)
	v_mfma_f32_32x32x16_bf16 v[112:127], v[244:247], v[168:171], v[112:127]
	v_add_f32_e32 v254, v254, v236
	v_add_f32_e32 v205, v205, v237
	v_cvt_pk_bf16_f32 v230, v230, v231
	v_cvt_pk_bf16_f32 v231, v232, v233
	s_waitcnt lgkmcnt(1)
	v_mfma_f32_32x32x16_bf16 v[96:111], v[248:251], v[172:175], v[96:111]
	v_cvt_pk_bf16_f32 v232, v234, v235
	v_cvt_pk_bf16_f32 v233, v236, v237
	v_add_f32_e32 v252, v252, v253
	s_waitcnt lgkmcnt(0)
	v_mfma_f32_32x32x16_bf16 v[112:127], v[8:11], v[172:175], v[112:127]
	v_add_f32_e32 v254, v254, v205
	v_add_f32_e32 v252, v252, v254
	v_add_f32_e32 v2, v2, v252
	s_setprio 0
	s_cmp_le_i32 s75, s68
	s_cbranch_scc1 .Lmaskdone_ab
	v_add_u32_e32 v0, s75, v201
	v_sub_u32_e32 v0, v0, v197
	s_nop 1
	v_cmp_ge_i32_e32 vcc, 63, v0
	v_cmp_gt_i32_e64 s[22:23], 63, v0
	v_cmp_ge_i32_e64 s[96:97], 61, v0
	v_cndmask_b32_e32 v96, v194, v96, vcc
	v_cndmask_b32_e64 v97, v194, v97, s[22:23]
	v_cndmask_b32_e64 v98, v194, v98, s[96:97]
	v_cmp_ge_i32_e32 vcc, 60, v0
	v_cmp_ge_i32_e64 s[22:23], 55, v0
	v_cmp_ge_i32_e64 s[96:97], 54, v0
	v_cndmask_b32_e32 v99, v194, v99, vcc
	v_cndmask_b32_e64 v100, v194, v100, s[22:23]
	v_cndmask_b32_e64 v101, v194, v101, s[96:97]
	v_cmp_ge_i32_e32 vcc, 53, v0
	v_cmp_ge_i32_e64 s[22:23], 52, v0
	v_cmp_ge_i32_e64 s[96:97], 47, v0
	v_cndmask_b32_e32 v102, v194, v102, vcc
	v_cndmask_b32_e64 v103, v194, v103, s[22:23]
	v_cndmask_b32_e64 v104, v194, v104, s[96:97]
	v_cmp_ge_i32_e32 vcc, 46, v0
	v_cmp_ge_i32_e64 s[22:23], 45, v0
	v_cmp_ge_i32_e64 s[96:97], 44, v0
	v_cndmask_b32_e32 v105, v194, v105, vcc
	v_cndmask_b32_e64 v106, v194, v106, s[22:23]
	v_cndmask_b32_e64 v107, v194, v107, s[96:97]
	v_cmp_ge_i32_e32 vcc, 39, v0
	v_cmp_ge_i32_e64 s[22:23], 38, v0
	v_cmp_ge_i32_e64 s[96:97], 37, v0
	v_cndmask_b32_e32 v108, v194, v108, vcc
	v_cndmask_b32_e64 v109, v194, v109, s[22:23]
	v_cndmask_b32_e64 v110, v194, v110, s[96:97]
	v_cmp_ge_i32_e32 vcc, 36, v0
	v_cmp_ge_i32_e64 s[22:23], 31, v0
	v_cmp_ge_i32_e64 s[96:97], 30, v0
	v_cndmask_b32_e32 v111, v194, v111, vcc
	v_cndmask_b32_e64 v112, v194, v112, s[22:23]
	v_cndmask_b32_e64 v113, v194, v113, s[96:97]
	v_cmp_ge_i32_e32 vcc, 29, v0
	v_cmp_ge_i32_e64 s[22:23], 28, v0
	v_cmp_ge_i32_e64 s[96:97], 23, v0
	v_cndmask_b32_e32 v114, v194, v114, vcc
	v_cndmask_b32_e64 v115, v194, v115, s[22:23]
	v_cndmask_b32_e64 v116, v194, v116, s[96:97]
	v_cmp_ge_i32_e32 vcc, 22, v0
	v_cmp_ge_i32_e64 s[22:23], 21, v0
	v_cmp_ge_i32_e64 s[96:97], 20, v0
	v_cndmask_b32_e32 v117, v194, v117, vcc
	v_cndmask_b32_e64 v118, v194, v118, s[22:23]
	v_cndmask_b32_e64 v119, v194, v119, s[96:97]
	v_cmp_ge_i32_e32 vcc, 15, v0
	v_cmp_ge_i32_e64 s[22:23], 14, v0
	v_cmp_ge_i32_e64 s[96:97], 13, v0
	v_cndmask_b32_e32 v120, v194, v120, vcc
	v_cndmask_b32_e64 v121, v194, v121, s[22:23]
	v_cndmask_b32_e64 v122, v194, v122, s[96:97]
	v_cmp_ge_i32_e32 vcc, 12, v0
	v_cmp_ge_i32_e64 s[22:23], 7, v0
	v_cmp_ge_i32_e64 s[96:97], 6, v0
	v_cndmask_b32_e32 v123, v194, v123, vcc
	v_cndmask_b32_e64 v124, v194, v124, s[22:23]
	v_cndmask_b32_e64 v125, v194, v125, s[96:97]
	v_cmp_ge_i32_e32 vcc, 5, v0
	v_cmp_ge_i32_e64 s[22:23], 4, v0
	s_nop 0
	v_cndmask_b32_e32 v126, v194, v126, vcc
	v_cndmask_b32_e64 v127, v194, v127, s[22:23]
